# v54: v53 + passB unit-2 gate loads issued in unit-1 tail ahead of the output stores; scan wait leaves the 8 stores outstanding
# speedup vs baseline: 1.0076x; 1.0076x over previous
; #define LAS __attribute__((address_space(3)))
; __device__ __forceinline__ unsigned cvt_pk_bf16(float lo, float hi) { unsigned r; asm volatile("v_cvt_pk_bf16_f32 %0, %1, %2" : "=v"(r) : "v"(lo), "v"(hi)); return r; }
; __device__ void passB_unit(const Params& p, LAS unsigned char* lds, int u, bool do_store = true) {
;     ...
;     __syncthreads();
; #pragma unroll
;     for (int mt = 0; mt < 4; ++mt) { const int t = wt2 * 64 + mt * 16 + fr;
;         const float tot = (ssP[t] + ssP[128 + t]) + (ssP[256 + t] + ssP[384 + t]); const float rinv = rsqrtf(tot * (1.0f / 256.0f) + 1e-6f);
; #pragma unroll
;         for (int nt = 0; nt < 4; ++nt) { const int v = w4 * 64 + nt * 16 + fq * 4; const f32x4 hw = *(const f32x4*)(p.head_norm_w + h * 256 + v);
;             const f32x4 o = hsum[mt][nt] * rinv * hw;
;             u32x2 w; w.x = cvt_pk_bf16(o[0], o[1]); w.y = cvt_pk_bf16(o[2], o[3]);
;             *(LAS u32x2*)(Pd + t * 264 + v) = w; } }
.LBB0_567:
	s_or_b64 exec, exec, s[0:1]
	v_readlane_b32 s80, v254, 6
	v_readlane_b32 s82, v254, 8
	v_readlane_b32 s83, v254, 9
	s_lshl_b32 s0, s34, 10
	s_mov_b64 s[54:55], s[82:83]
	v_lshl_or_b32 v50, v223, 6, v212
	s_add_u32 s42, s54, s0
	s_addc_u32 s43, s55, 0
	v_lshlrev_b32_e32 v52, 2, v50
	s_waitcnt lgkmcnt(0)
	s_barrier
	global_load_dwordx4 v[56:59], v52, s[42:43]
	global_load_dwordx4 v[60:63], v52, s[42:43] offset:64
	global_load_dwordx4 v[64:67], v52, s[42:43] offset:128
	global_load_dwordx4 v[68:71], v52, s[42:43] offset:192
	v_lshl_add_u32 v38, v211, 2, s49
	ds_read2st64_b32 v[36:37], v38 offset1:2
	ds_read2st64_b32 v[38:39], v38 offset0:4 offset1:6
	v_mov_b32_e32 v53, 0x358637bd
	s_mov_b32 s0, 0x800000
	v_lshlrev_b32_e32 v54, 1, v50
	s_waitcnt lgkmcnt(1)
	v_mov_b32_e32 v48, v36
	s_waitcnt lgkmcnt(0)
	v_mov_b32_e32 v49, v38
	v_mov_b32_e32 v38, v37
	v_pk_add_f32 v[36:37], v[48:49], v[38:39]
	v_add3_u32 v55, s46, v210, v54
	v_add_f32_e32 v36, v36, v37
	v_fmamk_f32 v36, v36, 0x3b800000, v53
	v_mul_f32_e32 v37, 0x4b800000, v36
	v_cmp_gt_f32_e32 vcc, s0, v36
	v_readlane_b32 s81, v254, 7
	v_readlane_b32 s84, v254, 10
	v_cndmask_b32_e32 v36, v36, v37, vcc
	v_rsq_f32_e32 v36, v36
	v_readlane_b32 s85, v254, 11
	v_readlane_b32 s86, v254, 12
	v_readlane_b32 s87, v254, 13
	v_mul_f32_e32 v37, 0x45800000, v36
	v_cndmask_b32_e32 v36, v36, v37, vcc
	v_pk_mul_f32 v[38:39], v[186:187], v[36:37] op_sel_hi:[1,0]
	v_pk_mul_f32 v[48:49], v[184:185], v[36:37] op_sel_hi:[1,0]
	v_pk_mul_f32 v[50:51], v[180:181], v[36:37] op_sel_hi:[1,0]
	v_readlane_b32 s88, v254, 14
	v_readlane_b32 s89, v254, 15
	v_readlane_b32 s90, v254, 16
	v_readlane_b32 s91, v254, 17
	v_readlane_b32 s92, v254, 18
	v_readlane_b32 s93, v254, 19
	v_readlane_b32 s94, v254, 20
	v_readlane_b32 s95, v254, 21
	s_waitcnt vmcnt(0)
	v_pk_mul_f32 v[26:27], v[58:59], v[48:49]
	v_pk_mul_f32 v[24:25], v[56:57], v[38:39]
	v_pk_mul_f32 v[48:49], v[182:183], v[36:37] op_sel_hi:[1,0]
	v_cvt_pk_bf16_f32 v38, v24, v25
	v_cvt_pk_bf16_f32 v39, v26, v27
	ds_write_b64 v55, v[38:39]
	s_waitcnt vmcnt(0)
	v_pk_mul_f32 v[26:27], v[62:63], v[50:51]
	v_pk_mul_f32 v[24:25], v[60:61], v[48:49]
	v_pk_mul_f32 v[48:49], v[106:107], v[36:37] op_sel_hi:[1,0]
	v_cvt_pk_bf16_f32 v38, v24, v25
	v_cvt_pk_bf16_f32 v39, v26, v27
	v_pk_mul_f32 v[50:51], v[104:105], v[36:37] op_sel_hi:[1,0]
	ds_write_b64 v55, v[38:39] offset:32
	s_waitcnt vmcnt(0)
	v_pk_mul_f32 v[26:27], v[66:67], v[50:51]
	v_pk_mul_f32 v[24:25], v[64:65], v[48:49]
	v_pk_mul_f32 v[48:49], v[98:99], v[36:37] op_sel_hi:[1,0]
	v_cvt_pk_bf16_f32 v38, v24, v25
	v_cvt_pk_bf16_f32 v39, v26, v27
	v_pk_mul_f32 v[36:37], v[96:97], v[36:37] op_sel_hi:[1,0]
	ds_write_b64 v55, v[38:39] offset:64
	v_lshl_add_u32 v38, v213, 2, s49
	s_waitcnt vmcnt(0)
	v_pk_mul_f32 v[26:27], v[36:37], v[70:71]
	v_pk_mul_f32 v[24:25], v[48:49], v[68:69]
	s_nop 0
	v_cvt_pk_bf16_f32 v36, v24, v25
	v_cvt_pk_bf16_f32 v37, v26, v27
	ds_write_b64 v55, v[36:37] offset:96
	ds_read2st64_b32 v[36:37], v38 offset1:2
	ds_read2st64_b32 v[38:39], v38 offset0:4 offset1:6
	v_add3_u32 v55, s46, v253, v54
	s_waitcnt lgkmcnt(1)
	v_mov_b32_e32 v48, v36
	s_waitcnt lgkmcnt(0)
	v_mov_b32_e32 v49, v38
	v_mov_b32_e32 v38, v37
	v_pk_add_f32 v[36:37], v[48:49], v[38:39]
	s_nop 0
	v_add_f32_e32 v36, v36, v37
	v_fmamk_f32 v36, v36, 0x3b800000, v53
	v_mul_f32_e32 v37, 0x4b800000, v36
	v_cmp_gt_f32_e32 vcc, s0, v36
	s_nop 1
	v_cndmask_b32_e32 v36, v36, v37, vcc
	v_rsq_f32_e32 v36, v36
	s_nop 0
	v_mul_f32_e32 v37, 0x45800000, v36
	v_cndmask_b32_e32 v36, v36, v37, vcc
	v_pk_mul_f32 v[38:39], v[110:111], v[36:37] op_sel_hi:[1,0]
	v_pk_mul_f32 v[48:49], v[108:109], v[36:37] op_sel_hi:[1,0]
	v_pk_mul_f32 v[50:51], v[100:101], v[36:37] op_sel_hi:[1,0]
	v_pk_mul_f32 v[46:47], v[46:47], v[36:37] op_sel_hi:[1,0]
	v_pk_mul_f32 v[44:45], v[44:45], v[36:37] op_sel_hi:[1,0]
	v_pk_mul_f32 v[42:43], v[42:43], v[36:37] op_sel_hi:[1,0]
	s_waitcnt vmcnt(0)
	v_pk_mul_f32 v[26:27], v[58:59], v[48:49]
	v_pk_mul_f32 v[24:25], v[56:57], v[38:39]
	v_pk_mul_f32 v[48:49], v[102:103], v[36:37] op_sel_hi:[1,0]
	v_cvt_pk_bf16_f32 v38, v24, v25
	v_cvt_pk_bf16_f32 v39, v26, v27
	ds_write_b64 v55, v[38:39]
	v_pk_mul_f32 v[36:37], v[40:41], v[36:37] op_sel_hi:[1,0]
	s_waitcnt vmcnt(0)
	v_pk_mul_f32 v[26:27], v[62:63], v[50:51]
	v_pk_mul_f32 v[24:25], v[60:61], v[48:49]
	s_nop 0
	v_cvt_pk_bf16_f32 v38, v24, v25
	v_cvt_pk_bf16_f32 v39, v26, v27
	ds_write_b64 v55, v[38:39] offset:32
	s_waitcnt vmcnt(0)
	v_pk_mul_f32 v[26:27], v[66:67], v[44:45]
	v_pk_mul_f32 v[24:25], v[64:65], v[46:47]
	s_nop 0
	v_cvt_pk_bf16_f32 v38, v24, v25
	v_cvt_pk_bf16_f32 v39, v26, v27
	ds_write_b64 v55, v[38:39] offset:64
	v_lshl_add_u32 v38, v214, 2, s49
	s_waitcnt vmcnt(0)
	v_pk_mul_f32 v[26:27], v[36:37], v[70:71]
	v_pk_mul_f32 v[24:25], v[42:43], v[68:69]
	s_nop 0
	v_cvt_pk_bf16_f32 v36, v24, v25
	v_cvt_pk_bf16_f32 v37, v26, v27
	ds_write_b64 v55, v[36:37] offset:96
	ds_read2st64_b32 v[36:37], v38 offset1:2
	ds_read2st64_b32 v[38:39], v38 offset0:4 offset1:6
	s_waitcnt lgkmcnt(1)
	v_mov_b32_e32 v40, v36
	s_waitcnt lgkmcnt(0)
	v_mov_b32_e32 v41, v38
	v_mov_b32_e32 v38, v37
	v_pk_add_f32 v[36:37], v[40:41], v[38:39]
	s_nop 0
	v_add_f32_e32 v36, v36, v37
	v_fmamk_f32 v36, v36, 0x3b800000, v53
	v_mul_f32_e32 v37, 0x4b800000, v36
	v_cmp_gt_f32_e32 vcc, s0, v36
	s_nop 1
	v_cndmask_b32_e32 v36, v36, v37, vcc
	v_rsq_f32_e32 v36, v36
	s_nop 0
	v_mul_f32_e32 v37, 0x45800000, v36
	v_cndmask_b32_e32 v36, v36, v37, vcc
	v_pk_mul_f32 v[32:33], v[32:33], v[36:37] op_sel_hi:[1,0]
	v_pk_mul_f32 v[34:35], v[34:35], v[36:37] op_sel_hi:[1,0]
	v_pk_mul_f32 v[22:23], v[22:23], v[36:37] op_sel_hi:[1,0]
	v_pk_mul_f32 v[20:21], v[20:21], v[36:37] op_sel_hi:[1,0]
	v_pk_mul_f32 v[18:19], v[18:19], v[36:37] op_sel_hi:[1,0]
	v_pk_mul_f32 v[14:15], v[14:15], v[36:37] op_sel_hi:[1,0]
	v_pk_mul_f32 v[10:11], v[10:11], v[36:37] op_sel_hi:[1,0]
	v_pk_mul_f32 v[8:9], v[8:9], v[36:37] op_sel_hi:[1,0]
	s_waitcnt vmcnt(0)
; #define LAS __attribute__((address_space(3)))
; __device__ __forceinline__ unsigned cvt_pk_bf16(float lo, float hi) { unsigned r; asm volatile("v_cvt_pk_bf16_f32 %0, %1, %2" : "=v"(r) : "v"(lo), "v"(hi)); return r; }
; __device__ void passB_unit(const Params& p, LAS unsigned char* lds, int u, bool do_store = true) {
;     ...
;     if (tid < 256) { const int d = tid >> 7, i = tid & 127; sc_t = d ? 127 - i : i;
;         sc_li = GL[(size_t)(d * 8 + h) * 2048 + sc_t]; float inc = GL[(size_t)(d * 8 + 4 + h) * 2048 + sc_t];
;     ...
;     for (int mt = 0; mt < 4; ++mt) { const int t = wt2 * 64 + mt * 16 + fr;
;         const float tot = (ssP[t] + ssP[128 + t]) + (ssP[256 + t] + ssP[384 + t]); const float rinv = rsqrtf(tot * (1.0f / 256.0f) + 1e-6f);
; #pragma unroll
;         for (int nt = 0; nt < 4; ++nt) { const int v = w4 * 64 + nt * 16 + fq * 4; const f32x4 hw = *(const f32x4*)(p.head_norm_w + h * 256 + v);
;             const f32x4 o = hsum[mt][nt] * rinv * hw;
;             u32x2 w; w.x = cvt_pk_bf16(o[0], o[1]); w.y = cvt_pk_bf16(o[2], o[3]);
;             *(LAS u32x2*)(Pd + t * 264 + v) = w; } }
;     __syncthreads();
;     __builtin_amdgcn_sched_barrier(0);
;     if (do_store) {
; #pragma unroll 2
;         for (int i = 0; i < 8; ++i) { const int id = tid + 512 * i; const int w = id >> 9, m = (id >> 7) & 3, bj = (id >> 6) & 1, ln = id & 63;
;             *(u32x4*)(Qg + (size_t)((w * 16 + m * 2 + bj) * 64 + ln) * 8) = *(const LAS u32x4*)(Pd + ((w >> 2) * 64 + m * 16 + (ln & 15)) * 264 + bj * 128 + (w & 3) * 32 + (ln >> 4) * 8); } }
	v_pk_mul_f32 v[26:27], v[58:59], v[34:35]
	v_pk_mul_f32 v[24:25], v[56:57], v[32:33]
	v_add3_u32 v34, s46, v252, v54
	v_cvt_pk_bf16_f32 v32, v24, v25
	v_cvt_pk_bf16_f32 v33, v26, v27
	ds_write_b64 v34, v[32:33]
	s_waitcnt vmcnt(0)
	v_pk_mul_f32 v[20:21], v[62:63], v[20:21]
	v_pk_mul_f32 v[22:23], v[60:61], v[22:23]
	s_nop 0
	v_cvt_pk_bf16_f32 v24, v22, v23
	v_cvt_pk_bf16_f32 v25, v20, v21
	ds_write_b64 v34, v[24:25] offset:32
	s_waitcnt vmcnt(0)
	v_pk_mul_f32 v[18:19], v[64:65], v[18:19]
	v_pk_mul_f32 v[14:15], v[66:67], v[14:15]
	v_cvt_pk_bf16_f32 v22, v18, v19
	s_nop 0
	v_cvt_pk_bf16_f32 v23, v14, v15
	ds_write_b64 v34, v[22:23] offset:64
	s_waitcnt vmcnt(0)
	v_pk_mul_f32 v[8:9], v[8:9], v[70:71]
	v_pk_mul_f32 v[10:11], v[10:11], v[68:69]
	v_lshl_add_u32 v18, v215, 2, s49
	v_cvt_pk_bf16_f32 v14, v10, v11
	v_cvt_pk_bf16_f32 v15, v8, v9
	ds_write_b64 v34, v[14:15] offset:96
	ds_read2st64_b32 v[14:15], v18 offset1:2
	ds_read2st64_b32 v[18:19], v18 offset0:4 offset1:6
	s_waitcnt lgkmcnt(1)
	v_mov_b32_e32 v20, v14
	s_waitcnt lgkmcnt(0)
	v_mov_b32_e32 v21, v18
	v_mov_b32_e32 v18, v15
	v_pk_add_f32 v[14:15], v[20:21], v[18:19]
	s_nop 0
	v_add_f32_e32 v14, v14, v15
	v_fmac_f32_e32 v53, 0x3b800000, v14
	v_mul_f32_e32 v14, 0x4b800000, v53
	v_cmp_gt_f32_e32 vcc, s0, v53
	s_mov_b32 s0, 0
	s_nop 0
	v_cndmask_b32_e32 v14, v53, v14, vcc
	v_rsq_f32_e32 v14, v14
	s_nop 0
	v_mul_f32_e32 v15, 0x45800000, v14
	v_cndmask_b32_e32 v14, v14, v15, vcc
	v_pk_mul_f32 v[18:19], v[28:29], v[14:15] op_sel_hi:[1,0]
	v_pk_mul_f32 v[20:21], v[30:31], v[14:15] op_sel_hi:[1,0]
	v_add3_u32 v15, s46, v227, v54
	v_pk_mul_f32 v[16:17], v[16:17], v[14:15] op_sel_hi:[1,0]
	v_pk_mul_f32 v[6:7], v[6:7], v[14:15] op_sel_hi:[1,0]
	v_pk_mul_f32 v[12:13], v[12:13], v[14:15] op_sel_hi:[1,0]
	v_pk_mul_f32 v[4:5], v[4:5], v[14:15] op_sel_hi:[1,0]
	v_pk_mul_f32 v[2:3], v[2:3], v[14:15] op_sel_hi:[1,0]
	v_pk_mul_f32 v[0:1], v[0:1], v[14:15] op_sel_hi:[1,0]
	s_waitcnt vmcnt(0)
	v_pk_mul_f32 v[10:11], v[58:59], v[20:21]
	v_pk_mul_f32 v[8:9], v[56:57], v[18:19]
	s_nop 0
	v_cvt_pk_bf16_f32 v18, v8, v9
	v_cvt_pk_bf16_f32 v19, v10, v11
	ds_write_b64 v15, v[18:19]
	s_waitcnt vmcnt(0)
	v_pk_mul_f32 v[6:7], v[62:63], v[6:7]
	v_pk_mul_f32 v[8:9], v[60:61], v[16:17]
	s_nop 0
	v_cvt_pk_bf16_f32 v10, v8, v9
	v_cvt_pk_bf16_f32 v11, v6, v7
	ds_write_b64 v15, v[10:11] offset:32
	s_waitcnt vmcnt(0)
	v_pk_mul_f32 v[4:5], v[66:67], v[4:5]
	v_pk_mul_f32 v[6:7], v[64:65], v[12:13]
	s_nop 0
	v_cvt_pk_bf16_f32 v8, v6, v7
	v_cvt_pk_bf16_f32 v9, v4, v5
	ds_write_b64 v15, v[8:9] offset:64
	s_waitcnt vmcnt(0)
	v_pk_mul_f32 v[0:1], v[0:1], v[70:71]
	v_pk_mul_f32 v[2:3], v[2:3], v[68:69]
	s_nop 0
	v_cvt_pk_bf16_f32 v2, v2, v3
	v_cvt_pk_bf16_f32 v3, v0, v1
	ds_write_b64 v15, v[2:3] offset:96
	s_waitcnt lgkmcnt(0)
	s_barrier
	v_cmp_gt_u32_e32 vcc, 0x100, v224
	s_and_saveexec_b64 s[62:63], vcc
	s_ashr_i32 s65, s40, 31
	s_mov_b32 s64, s40
	s_lshl_b64 s[64:65], s[64:65], 17
	s_add_u32 s64, s70, s64
	s_addc_u32 s65, s71, s65
	s_or_b32 s66, s52, 1
	s_lshl_b32 s66, s66, 9
	s_add_u32 s64, s64, s66
	s_addc_u32 s65, s65, 0
	s_add_u32 s64, s64, 0xfc00000
	s_addc_u32 s65, s65, 0
	s_movk_i32 s67, 0x7f
	v_and_b32_e32 v74, 0x7f, v224
	v_bitop3_b32 v75, v224, s67, v224 bitop3:0xc
	v_cmp_gt_u32_e32 vcc, 0x80, v224
	s_nop 1
	v_cndmask_b32_e32 v74, v75, v74, vcc
	v_ashrrev_i32_e32 v75, 4, v224
	v_and_or_b32 v75, v75, -8, s34
	v_or_b32_e32 v76, 4, v75
	v_ashrrev_i32_e32 v77, 31, v76
	v_lshlrev_b64 v[76:77], 13, v[76:77]
	v_lshlrev_b32_e32 v78, 2, v74
	v_mov_b32_e32 v79, 0
	v_lshl_add_u64 v[76:77], s[64:65], 0, v[76:77]
	v_lshl_add_u64 v[76:77], v[76:77], 0, v[78:79]
	global_load_dword v72, v[76:77], off
	v_mov_b32_e32 v80, v75
	v_ashrrev_i32_e32 v81, 31, v75
	v_lshlrev_b64 v[80:81], 13, v[80:81]
	v_lshl_add_u64 v[80:81], s[64:65], 0, v[80:81]
	v_lshl_add_u64 v[80:81], v[80:81], 0, v[78:79]
	global_load_dword v73, v[80:81], off
	s_or_b64 exec, exec, s[62:63]
	v_or_b32_e32 v2, v198, v199
	v_add_u32_e32 v0, s46, v203
	v_or_b32_e32 v1, v202, v201
	s_mov_b32 s1, 0xfffffc0
	s_movk_i32 s4, 0x210
	v_lshlrev_b32_e32 v2, 6, v2
; #define LAS __attribute__((address_space(3)))
; __device__ void passB_unit(const Params& p, LAS unsigned char* lds, int u, bool do_store = true) {
;     ...
;     float sc_b = 0.f, sc_li = 0.f; int sc_t = 0;
;     if (tid < 256) { const int d = tid >> 7, i = tid & 127; sc_t = d ? 127 - i : i;
;         sc_li = GL[(size_t)(d * 8 + h) * 2048 + sc_t]; float inc = GL[(size_t)(d * 8 + 4 + h) * 2048 + sc_t];
; #pragma unroll
;         for (int off = 1; off < 64; off <<= 1) { const float n = __shfl_up(inc, off); inc += (lane >= off) ? n : 0.f; }
;         sc_b = inc; if (lane == 63) wtot[wid] = inc; }
;     ...
;         for (int i = 0; i < 8; ++i) { const int id = tid + 512 * i; const int w = id >> 9, m = (id >> 7) & 3, bj = (id >> 6) & 1, ln = id & 63;
;             *(u32x4*)(Qg + (size_t)((w * 16 + m * 2 + bj) * 64 + ln) * 8) = *(const LAS u32x4*)(Pd + ((w >> 2) * 64 + m * 16 + (ln & 15)) * 264 + bj * 128 + (w & 3) * 32 + (ln >> 4) * 8); } }
.LBB0_568:
	v_add_u32_e32 v3, s0, v196
	v_ashrrev_i32_e32 v5, 5, v3
	v_ashrrev_i32_e32 v4, 9, v3
	v_add_u32_e32 v3, 0x200, v3
	v_and_or_b32 v5, v5, s1, v1
	v_lshlrev_b32_e32 v6, 6, v4
	v_lshlrev_b32_e32 v7, 10, v4
	v_ashrrev_i32_e32 v8, 9, v3
	v_ashrrev_i32_e32 v3, 5, v3
	v_mad_u64_u32 v[4:5], s[6:7], v5, s4, v[0:1]
	v_and_b32_e32 v5, 0xc0, v6
	v_and_or_b32 v3, v3, s1, v1
	v_lshlrev_b32_e32 v6, 6, v8
	v_or3_b32 v12, v7, v2, v197
	v_lshlrev_b32_e32 v7, 10, v8
	v_add3_u32 v8, v4, v5, v200
	v_mad_u64_u32 v[4:5], s[6:7], v3, s4, v[0:1]
	v_and_b32_e32 v3, 0xc0, v6
	v_or3_b32 v14, v7, v2, v197
	v_add3_u32 v3, v4, v3, v200
	ds_read_b128 v[4:7], v8
	ds_read_b128 v[8:11], v3
	s_addk_i32 s0, 0x400
	v_ashrrev_i32_e32 v13, 31, v12
	s_cmpk_lg_i32 s0, 0x1000
	v_lshl_add_u64 v[12:13], v[12:13], 4, s[44:45]
	v_ashrrev_i32_e32 v15, 31, v14
	v_lshl_add_u64 v[14:15], v[14:15], 4, s[44:45]
	s_waitcnt lgkmcnt(1)
	global_store_dwordx4 v[12:13], v[4:7], off
	s_waitcnt lgkmcnt(0)
	global_store_dwordx4 v[14:15], v[8:11], off
	s_cbranch_scc1 .LBB0_568
	v_mov_b32_e32 v196, v224
	s_or_b32 s24, s52, 1
	s_movk_i32 s0, 0x100
	s_barrier
	s_lshl_b32 s10, s24, 7
	v_ashrrev_i32_e32 v68, 6, v196
	v_and_b32_e32 v197, 63, v196
	v_cmp_gt_i32_e64 s[0:1], s0, v196
	v_mov_b32_e32 v63, 0
	v_mov_b32_e32 v69, 0
	v_add_u32_e32 v5, -1, v204
	v_add_u32_e32 v4, -2, v204
	v_add_u32_e32 v3, -4, v204
	v_add_u32_e32 v2, -8, v204
	v_add_u32_e32 v1, -16, v204
	v_subrev_u32_e32 v0, 32, v204
	v_mov_b32_e32 v6, 0
	s_and_saveexec_b64 s[4:5], s[0:1]
	s_cbranch_execz .LBB0_573
	s_ashr_i32 s41, s40, 31
	s_lshl_b64 s[6:7], s[40:41], 17
	s_add_u32 s6, s70, s6
	s_addc_u32 s7, s71, s7
	s_lshl_b32 s11, s10, 2
	s_add_u32 s6, s6, s11
	s_movk_i32 s11, 0x7f
	s_movk_i32 s25, 0x80
	v_and_b32_e32 v6, 0x7f, v196
	v_bitop3_b32 v7, v196, s11, v196 bitop3:0xc
	v_cmp_gt_u32_e32 vcc, s25, v196
	s_addc_u32 s7, s7, 0
	s_add_u32 s6, s6, 0xfc00000
	v_cndmask_b32_e32 v63, v7, v6, vcc
	v_ashrrev_i32_e32 v6, 4, v196
	v_and_or_b32 v6, v6, -8, s34
	v_or_b32_e32 v10, 4, v6
	v_ashrrev_i32_e32 v11, 31, v10
	s_addc_u32 s7, s7, 0
	v_lshlrev_b64 v[10:11], 13, v[10:11]
	v_lshlrev_b32_e32 v8, 2, v63
	v_mov_b32_e32 v9, 0
	v_lshl_add_u64 v[10:11], s[6:7], 0, v[10:11]
	v_lshl_add_u64 v[10:11], v[10:11], 0, v[8:9]
	v_ashrrev_i32_e32 v7, 31, v6
	v_lshlrev_b64 v[6:7], 13, v[6:7]
	v_lshl_add_u64 v[6:7], s[6:7], 0, v[6:7]
	v_lshl_add_u64 v[6:7], v[6:7], 0, v[8:9]
	s_waitcnt vmcnt(8)
	v_mov_b32_e32 v10, v72
	v_mov_b32_e32 v6, v73
	s_nop 1
	v_add_f32_dpp v10, v10, v10 row_shr:1 row_mask:0xf bank_mask:0xf
	s_nop 1
	v_add_f32_dpp v10, v10, v10 row_shr:2 row_mask:0xf bank_mask:0xf
	s_nop 1
	v_add_f32_dpp v10, v10, v10 row_shr:4 row_mask:0xf bank_mask:0xf
	s_nop 1
	v_add_f32_dpp v10, v10, v10 row_shr:8 row_mask:0xf bank_mask:0xf
	s_nop 1
	v_add_f32_dpp v10, v10, v10 row_bcast:15 row_mask:0xa bank_mask:0xf
	s_nop 1
	v_add_f32_dpp v10, v10, v10 row_bcast:31 row_mask:0xc bank_mask:0xf
	v_mov_b32_e32 v69, v10
	v_cmp_eq_u32_e32 vcc, 63, v197
	s_and_saveexec_b64 s[6:7], vcc
	v_lshl_add_u32 v7, v68, 2, 0
	v_add_u32_e32 v7, 0x21800, v7
	ds_write_b32 v7, v69
	s_or_b64 exec, exec, s[6:7]
